# v49 + odd-C loop wait relaxed to vmcnt(2): does not drain the previous unit's stores
# speedup vs baseline: 1.0059x; 1.0026x over previous
; #define LAS __attribute__((address_space(3)))
; DI void phase_odd_c(const Params& p, LAS unsigned char* lds, int tid_, int wave, int G) {
;     unsigned char* ws = p.ws;
;     const bf16* PROJ = (const bf16*)(ws + WS_PROJ); const bf16* OR = (const bf16*)(ws + WS_OR); bf16* AO = (bf16*)(ws + WS_AO);
;     LAS bf16* Ot = (LAS bf16*)lds;
;     int tid = tid_; asm volatile("" : "+v"(tid));
;     const int tl = tid >> 3, part = tid & 7;
;     const float* og = (const float*)p.in[I_DOG] + part * 16;
;     const f32x4 g0 = *(const f32x4*)og, g1 = *(const f32x4*)(og + 4), g2 = *(const f32x4*)(og + 8), g3 = *(const f32x4*)(og + 12);
;     const float gg[16] = {g0[0], g0[1], g0[2], g0[3], g1[0], g1[1], g1[2], g1[3], g2[0], g2[1], g2[2], g2[3], g3[0], g3[1], g3[2], g3[3]};
;     constexpr int NU = NB_P * 64 * DNH;
;     u32x4 orn[2], zn[2];
;     { const int u0 = (int)blockIdx.x < NU ? (int)blockIdx.x : 0; const int h = u0 & 7, c = (u0 >> 3) & 63, b = u0 >> 9; const size_t m = (size_t)(b * T_P + c * 64 + tl);
; #pragma unroll
;       for (int rep = 0; rep < 2; ++rep) orn[rep] = *(const u32x4*)(OR + (size_t)u0 * 8192 + (size_t)(tid + 512 * rep) * 8);
;       zn[0] = *(const u32x4*)(PROJ + m * ODD_PAD + 3 * DNW + h * DND + part * 16); zn[1] = *(const u32x4*)(PROJ + m * ODD_PAD + 3 * DNW + h * DND + part * 16 + 8); }
;     for (int unit = blockIdx.x; unit < NU; unit += G) {
;         const int h = unit & 7, c = (unit >> 3) & 63, b = unit >> 9, m0 = b * T_P + c * 64;
;         const u32x4 z0 = zn[0], z1 = zn[1];
.LBB0_1874:
	s_cmp_lt_i32 s28, 16
	s_cselect_b64 s[4:5], -1, 0
	s_and_b64 s[0:1], s[4:5], s[0:1]
	s_andn2_b64 vcc, exec, s[0:1]
	s_cbranch_vccnz .LBB0_1878
	v_readlane_b32 s0, v244, 60
	s_waitcnt vmcnt(0)
	v_mov_b32_e32 v40, v0
	s_cmpk_gt_i32 s0, 0x7ff
	v_readlane_b32 s1, v244, 61
	s_cbranch_scc1 .LBB0_1878
	v_readlane_b32 s8, v244, 3
	v_readlane_b32 s14, v244, 9
	v_readlane_b32 s15, v244, 10
	s_add_u32 s2, s14, 0x27c00000
	s_addc_u32 s3, s15, 0
	v_readlane_b32 s14, v244, 60
	v_readlane_b32 s21, v244, 62
	v_readlane_b32 s15, v244, 61
	v_ashrrev_i32_e32 v1, 3, v40
	s_and_b32 s0, s21, 0xffffffc0
	s_ashr_i32 s15, s14, 31
	v_add_u32_e32 v44, 0x200, v40
	v_add_u32_e32 v30, s0, v1
	s_lshl_b64 s[0:1], s[14:15], 14
	v_lshlrev_b32_e32 v43, 4, v40
	v_ashrrev_i32_e32 v45, 31, v44
	s_add_u32 s0, s2, s0
	v_and_b32_e32 v42, 0x70, v43
	v_ashrrev_i32_e32 v41, 31, v40
	v_lshlrev_b64 v[38:39], 4, v[44:45]
	s_addc_u32 s1, s3, s1
	v_readlane_b32 s22, v243, 6
	v_readlane_b32 s9, v244, 4
	v_readlane_b32 s10, v244, 5
	v_lshlrev_b64 v[36:37], 4, v[40:41]
	v_lshlrev_b32_e32 v18, 2, v42
	v_lshl_add_u64 v[26:27], s[0:1], 0, v[38:39]
	v_readlane_b32 s23, v243, 7
	s_waitcnt lgkmcnt(0)
	global_load_dwordx4 v[2:5], v18, s[8:9]
	global_load_dwordx4 v[6:9], v18, s[8:9] offset:16
	global_load_dwordx4 v[10:13], v18, s[8:9] offset:32
	global_load_dwordx4 v[14:17], v18, s[8:9] offset:48
	v_lshl_add_u64 v[28:29], s[0:1], 0, v[36:37]
	global_load_dwordx4 v[18:21], v[26:27], off
	global_load_dwordx4 v[22:25], v[28:29], off
	s_movk_i32 s10, 0x2200
	v_mov_b64_e32 v[26:27], s[22:23]
	v_mad_i64_i32 v[26:27], s[0:1], v30, s10, v[26:27]
	s_lshl_b32 s0, s14, 8
	s_mov_b32 s7, 0
	s_and_b32 s6, s0, 0x700
	v_readlane_b32 s11, v244, 6
	v_mov_b32_e32 v35, 0
	v_lshlrev_b32_e32 v34, 1, v42
	v_lshl_add_u64 v[26:27], v[26:27], 0, s[6:7]
	v_lshl_add_u64 v[26:27], v[26:27], 0, v[34:35]
	s_movk_i32 s11, 0x1000
	v_add_co_u32_e32 v48, vcc, s11, v26
	s_mov_b64 s[8:9], 0x1800
	s_nop 0
	v_addc_co_u32_e32 v49, vcc, 0, v27, vcc
	v_lshl_add_u64 v[46:47], v[26:27], 0, s[8:9]
	global_load_dwordx4 v[26:29], v[48:49], off offset:2048
	global_load_dwordx4 v[30:33], v[46:47], off offset:16
	v_add_u32_e32 v41, 0, v34
	v_and_b32_e32 v34, 16, v43
	v_lshrrev_b32_e32 v43, 2, v40
	v_and_b32_e32 v43, 32, v43
	v_lshrrev_b32_e32 v45, 4, v40
	v_and_b32_e32 v40, 62, v40
	v_lshlrev_b32_e32 v48, 1, v1
	v_and_or_b32 v43, v45, 4, v43
	v_add_u32_e32 v40, 0, v40
	v_and_b32_e32 v48, 0xffffffc0, v48
	v_add_u32_e32 v50, v40, v48
	v_or_b32_e32 v48, v43, v34
	v_mul_u32_u24_e32 v51, 0x110, v48
	v_or_b32_e32 v48, 1, v43
	v_or_b32_e32 v49, v48, v34
	v_mul_u32_u24_e32 v52, 0x110, v49
	v_or_b32_e32 v49, 2, v43
	v_or_b32_e32 v58, 3, v43
	v_or_b32_e32 v53, v49, v34
	v_or_b32_e32 v54, v58, v34
	v_or_b32_e32 v34, 8, v34
	v_or_b32_e32 v43, v43, v34
	v_mul_u32_u24_e32 v55, 0x110, v43
	v_or_b32_e32 v43, v48, v34
	v_mul_u32_u24_e32 v56, 0x110, v43
	v_or_b32_e32 v43, v49, v34
	v_or_b32_e32 v34, v58, v34
	v_mbcnt_lo_u32_b32 v46, -1, 0
	v_mul_u32_u24_e32 v58, 0x110, v34
	v_ashrrev_i32_e32 v34, 3, v44
	v_mbcnt_hi_u32_b32 v46, -1, v46
	v_lshlrev_b32_e32 v34, 1, v34
	v_and_b32_e32 v47, 64, v46
	v_and_b32_e32 v34, 0xffffffc0, v34
	v_add_u32_e32 v47, 64, v47
	v_add_u32_e32 v59, v40, v34
	v_xor_b32_e32 v34, 1, v46
	v_cmp_lt_i32_e32 vcc, v34, v47
	s_movk_i32 s0, 0x110
	v_readlane_b32 s13, v244, 8
	v_cndmask_b32_e32 v34, v46, v34, vcc
	v_lshlrev_b32_e32 v60, 2, v34
	v_xor_b32_e32 v34, 2, v46
	v_cmp_lt_i32_e32 vcc, v34, v47
	v_mul_lo_u32 v45, v1, s0
	v_readlane_b32 s0, v244, 2
	v_cndmask_b32_e32 v34, v46, v34, vcc
	v_lshlrev_b32_e32 v61, 2, v34
	v_xor_b32_e32 v34, 4, v46
	s_lshl_b32 s13, s0, 7
	s_mov_b32 s0, s14
	v_readlane_b32 s12, v244, 7
	v_cmp_lt_i32_e32 vcc, v34, v47
	v_writelane_b32 v244, s0, 60
	v_readlane_b32 s24, v243, 24
	v_cndmask_b32_e32 v34, v46, v34, vcc
	v_writelane_b32 v244, s1, 61
	s_lshl_b32 s12, s14, 7
	v_mul_u32_u24_e32 v53, 0x110, v53
	v_mul_u32_u24_e32 v54, 0x110, v54
	v_mul_u32_u24_e32 v57, 0x110, v43
	v_lshlrev_b32_e32 v62, 2, v34
	v_lshlrev_b32_e32 v34, 1, v42
	v_add_u32_e32 v63, v41, v45
	v_mov_b32_e32 v64, 0x358637bd
	v_readlane_b32 s20, v244, 59
	v_readlane_b32 s25, v243, 25
	s_waitcnt vmcnt(0)
.LBB0_1877:
	v_readlane_b32 s0, v244, 2
	s_add_i32 s0, s14, s0
	v_add_u32_e32 v65, v50, v51
	v_add_u32_e32 v68, v50, v52
	v_add_u32_e32 v71, v50, v55
	v_add_u32_e32 v72, v50, v56
	s_waitcnt vmcnt(2)
; DI void phase_odd_c(const Params& p, LAS unsigned char* lds, int tid_, int wave, int G) {
;     ...
; #pragma unroll
;         for (int rep = 0; rep < 2; ++rep) { const int q = tid + 512 * rep;
;             const int half = q & 1, lane = (q >> 1) & 63, ti = (q >> 7) & 1, w = q >> 8, r = lane & 31, h2 = lane >> 5;
;             const u32x4 v = orn[rep];
; #pragma unroll
;             for (int j = 0; j < 8; ++j) { const int i = 8 * half + j, tok = 32 * ti + (i & 3) + 8 * (i >> 2) + 4 * h2;
;                 Ot[tok * QLD + 32 * w + r] = (bf16)((j & 1) ? (v[j >> 1] >> 16) : (v[j >> 1] & 0xffffu)); } }
;         { const int un = unit + G < NU ? unit + G : unit; const int hn = un & 7, cn = (un >> 3) & 63, bn = un >> 9; const size_t mn = (size_t)(bn * T_P + cn * 64 + tl);
; #pragma unroll
;           for (int rep = 0; rep < 2; ++rep) orn[rep] = *(const u32x4*)(OR + (size_t)un * 8192 + (size_t)(tid + 512 * rep) * 8);
;           zn[0] = *(const u32x4*)(PROJ + mn * ODD_PAD + 3 * DNW + hn * DND + part * 16); zn[1] = *(const u32x4*)(PROJ + mn * ODD_PAD + 3 * DNW + hn * DND + part * 16 + 8); }
;         const size_t m = m0 + tl;
;         __syncthreads();
	v_lshlrev_b32_e32 v42, 16, v33
	v_and_b32_e32 v43, 0xffff0000, v33
	v_lshlrev_b32_e32 v66, 16, v30
	v_and_b32_e32 v67, 0xffff0000, v30
	s_cmpk_lt_i32 s0, 0x800
	v_add_u32_e32 v69, v50, v53
	v_add_u32_e32 v70, v50, v54
	v_add_u32_e32 v73, v50, v57
	v_add_u32_e32 v74, v50, v58
	v_add_u32_e32 v75, v59, v51
	v_add_u32_e32 v76, v59, v52
	v_add_u32_e32 v77, v59, v53
	v_add_u32_e32 v78, v59, v54
	v_add_u32_e32 v79, v59, v55
	v_add_u32_e32 v80, v59, v56
	v_add_u32_e32 v81, v59, v57
	v_add_u32_e32 v82, v59, v58
	v_lshlrev_b32_e32 v44, 16, v29
	v_and_b32_e32 v45, 0xffff0000, v29
	ds_write_b16 v65, v22
	ds_write_b16_d16_hi v68, v22
	ds_write_b16 v69, v23
	ds_write_b16_d16_hi v70, v23
	ds_write_b16 v71, v24
	ds_write_b16_d16_hi v72, v24
	ds_write_b16 v73, v25
	ds_write_b16_d16_hi v74, v25
	ds_write_b16 v75, v18
	ds_write_b16_d16_hi v76, v18
	ds_write_b16 v77, v19
	ds_write_b16_d16_hi v78, v19
	ds_write_b16 v79, v20
	ds_write_b16_d16_hi v80, v20
	ds_write_b16 v81, v21
	ds_write_b16_d16_hi v82, v21
	v_mul_f32_e32 v65, 0xbfb8aa3b, v66
	v_mul_f32_e32 v68, 0xbfb8aa3b, v67
	v_mul_f32_e32 v71, 0xbfb8aa3b, v42
	v_mul_f32_e32 v72, 0xbfb8aa3b, v43
	s_cselect_b64 s[16:17], -1, 0
	v_lshlrev_b32_e32 v46, 16, v32
	v_and_b32_e32 v47, 0xffff0000, v32
	v_lshlrev_b32_e32 v32, 16, v28
	v_and_b32_e32 v33, 0xffff0000, v28
	v_lshlrev_b32_e32 v28, 16, v31
	v_and_b32_e32 v29, 0xffff0000, v31
	v_lshlrev_b32_e32 v48, 16, v27
	v_and_b32_e32 v49, 0xffff0000, v27
	v_lshlrev_b32_e32 v30, 16, v26
	v_and_b32_e32 v31, 0xffff0000, v26
	v_mul_f32_e32 v18, 0xbfb8aa3b, v44
	v_mul_f32_e32 v19, 0xbfb8aa3b, v45
	v_exp_f32_e32 v65, v65
	v_exp_f32_e32 v68, v68
	v_exp_f32_e32 v71, v71
	v_exp_f32_e32 v72, v72
	s_and_b64 vcc, s[16:17], exec
	v_mul_f32_e32 v22, 0xbfb8aa3b, v32
	v_mul_f32_e32 v23, 0xbfb8aa3b, v33
	v_mul_f32_e32 v24, 0xbfb8aa3b, v28
	v_mul_f32_e32 v25, 0xbfb8aa3b, v29
	v_mul_f32_e32 v26, 0xbfb8aa3b, v48
	v_mul_f32_e32 v27, 0xbfb8aa3b, v49
	v_mul_f32_e32 v69, 0xbfb8aa3b, v30
	v_mul_f32_e32 v70, 0xbfb8aa3b, v31
	v_exp_f32_e32 v18, v18
	v_exp_f32_e32 v19, v19
	s_cselect_b32 s16, s0, s14
	v_exp_f32_e32 v22, v22
	v_exp_f32_e32 v23, v23
	v_exp_f32_e32 v24, v24
	v_exp_f32_e32 v25, v25
	v_exp_f32_e32 v26, v26
	v_exp_f32_e32 v27, v27
	v_exp_f32_e32 v69, v69
	v_exp_f32_e32 v70, v70
	s_mov_b32 s14, s0
	s_lshl_b32 s0, s16, 3
	s_ashr_i32 s17, s16, 31
	s_and_b32 s6, s0, 0xffffffc0
	s_lshl_b64 s[0:1], s[16:17], 14
	v_mul_f32_e32 v20, 0xbfb8aa3b, v46
	v_mul_f32_e32 v21, 0xbfb8aa3b, v47
	v_add_f32_e32 v65, 1.0, v65
	v_add_f32_e32 v77, 1.0, v68
	v_add_f32_e32 v80, 1.0, v71
	v_add_f32_e32 v81, 1.0, v72
	s_add_u32 s0, s2, s0
	v_mov_b64_e32 v[40:41], s[22:23]
	v_exp_f32_e32 v20, v20
	v_exp_f32_e32 v21, v21
	v_add_f32_e32 v18, 1.0, v18
	v_add_f32_e32 v19, 1.0, v19
	v_add_u32_e32 v82, s6, v1
	v_rcp_f32_e32 v76, v65
	v_rcp_f32_e32 v77, v77
	v_rcp_f32_e32 v80, v80
	v_rcp_f32_e32 v81, v81
	s_addc_u32 s1, s3, s1
	s_lshl_b32 s6, s16, 8
	v_add_f32_e32 v22, 1.0, v22
	v_add_f32_e32 v23, 1.0, v23
	v_add_f32_e32 v24, 1.0, v24
	v_add_f32_e32 v25, 1.0, v25
	v_add_f32_e32 v74, 1.0, v26
	v_add_f32_e32 v75, 1.0, v27
	v_add_f32_e32 v78, 1.0, v69
	v_add_f32_e32 v79, 1.0, v70
	v_rcp_f32_e32 v26, v18
	v_rcp_f32_e32 v27, v19
	v_mad_i64_i32 v[40:41], s[18:19], v82, s10, v[40:41]
	s_and_b32 s6, s6, 0x700
	v_rcp_f32_e32 v70, v22
	v_rcp_f32_e32 v71, v23
	v_rcp_f32_e32 v72, v24
	v_rcp_f32_e32 v73, v25
	v_rcp_f32_e32 v74, v74
	v_rcp_f32_e32 v75, v75
	v_rcp_f32_e32 v78, v78
	v_rcp_f32_e32 v79, v79
	s_and_b32 s15, s21, 0xffffffc0
	v_lshl_add_u64 v[40:41], v[40:41], 0, s[6:7]
	v_add_u32_e32 v86, s15, v1
	v_lshl_add_u64 v[40:41], v[40:41], 0, v[34:35]
	v_add_f32_e32 v20, 1.0, v20
	v_add_f32_e32 v21, 1.0, v21
	v_lshl_add_u64 v[82:83], s[0:1], 0, v[36:37]
	v_lshl_add_u64 v[84:85], s[0:1], 0, v[38:39]
	v_ashrrev_i32_e32 v87, 31, v86
	v_pk_mul_f32 v[66:67], v[76:77], v[66:67]
	v_pk_mul_f32 v[76:77], v[80:81], v[42:43]
	v_lshl_add_u64 v[42:43], v[40:41], 0, s[8:9]
	v_add_co_u32_e64 v40, s[0:1], s11, v40
	v_rcp_f32_e32 v68, v20
	v_rcp_f32_e32 v69, v21
	global_load_dwordx4 v[22:25], v[82:83], off
	global_load_dwordx4 v[18:21], v[84:85], off
	v_pk_mul_f32 v[82:83], v[26:27], v[44:45]
	v_lshlrev_b64 v[26:27], 11, v[86:87]
	v_addc_co_u32_e64 v41, s[0:1], 0, v41, s[0:1]
	v_pk_mul_f32 v[70:71], v[70:71], v[32:33]
	v_pk_mul_f32 v[72:73], v[72:73], v[28:29]
	v_pk_mul_f32 v[48:49], v[74:75], v[48:49]
	v_pk_mul_f32 v[74:75], v[78:79], v[30:31]
	v_lshl_add_u64 v[78:79], s[24:25], 0, v[26:27]
	global_load_dwordx4 v[26:29], v[40:41], off offset:2048
	global_load_dwordx4 v[30:33], v[42:43], off offset:16
	v_pk_mul_f32 v[68:69], v[68:69], v[46:47]
	s_waitcnt lgkmcnt(0)
	s_barrier
; #define LAS __attribute__((address_space(3)))
; DI unsigned pk2(float lo, float hi) { f32x2 v = {lo, hi}; return __builtin_bit_cast(unsigned, __builtin_convertvector(v, bf16v2)); }
; DI float frsq(float x) { return __builtin_amdgcn_rsqf(x); }
; DI float fsilu(float x) { return x * fsigmoid(x); }
; DI void phase_odd_c(const Params& p, LAS unsigned char* lds, int tid_, int wave, int G) {
;     ...
;         const u32x4 o0 = *(const LAS u32x4*)(Ot + tl * QLD + part * 16), o1 = *(const LAS u32x4*)(Ot + tl * QLD + part * 16 + 8);
;         float o[16], z[16];
; #pragma unroll
;         for (int j = 0; j < 4; ++j) { o[2 * j] = bflo(o0[j]); o[2 * j + 1] = bfhi(o0[j]); o[8 + 2 * j] = bflo(o1[j]); o[8 + 2 * j + 1] = bfhi(o1[j]);
;             z[2 * j] = bflo(z0[j]); z[2 * j + 1] = bfhi(z0[j]); z[8 + 2 * j] = bflo(z1[j]); z[8 + 2 * j + 1] = bfhi(z1[j]); }
;         float ss = 0.f;
; #pragma unroll
;         for (int j = 0; j < 16; ++j) ss += o[j] * o[j];
; #pragma unroll
;         for (int of = 1; of < 8; of <<= 1) ss += __shfl_xor(ss, of);
;         const float rn = frsq(ss * (1.f / DND) + EPS);
;         u32x4 w0, w1;
; #pragma unroll
;         for (int j = 0; j < 4; ++j) { w0[j] = pk2(o[2 * j] * rn * gg[2 * j] * fsilu(z[2 * j]), o[2 * j + 1] * rn * gg[2 * j + 1] * fsilu(z[2 * j + 1]));
;             w1[j] = pk2(o[8 + 2 * j] * rn * gg[8 + 2 * j] * fsilu(z[8 + 2 * j]), o[8 + 2 * j + 1] * rn * gg[8 + 2 * j + 1] * fsilu(z[8 + 2 * j + 1])); }
;         bf16* dst = AO + m * DM + h * DND + part * 16; *(u32x4*)dst = w0; *(u32x4*)(dst + 8) = w1;
;         __syncthreads();
;     }
	ds_read_b128 v[40:43], v63 offset:16
	ds_read_b128 v[44:47], v63
	s_and_b32 s16, s12, 0x380
	s_lshl_b32 s6, s16, 1
	v_lshl_add_u64 v[78:79], v[78:79], 0, s[6:7]
	s_waitcnt lgkmcnt(1)
	v_lshlrev_b32_e32 v80, 16, v43
	v_and_b32_e32 v81, 0xffff0000, v43
	s_waitcnt lgkmcnt(0)
	v_lshlrev_b32_e32 v84, 16, v47
	v_and_b32_e32 v85, 0xffff0000, v47
	v_lshlrev_b32_e32 v86, 16, v42
	v_and_b32_e32 v87, 0xffff0000, v42
	v_lshlrev_b32_e32 v42, 16, v46
	v_and_b32_e32 v43, 0xffff0000, v46
	v_lshlrev_b32_e32 v46, 16, v41
	v_and_b32_e32 v47, 0xffff0000, v41
	v_lshlrev_b32_e32 v90, 16, v40
	v_and_b32_e32 v91, 0xffff0000, v40
	v_lshlrev_b32_e32 v40, 16, v44
	v_and_b32_e32 v41, 0xffff0000, v44
	v_lshlrev_b32_e32 v88, 16, v45
	v_and_b32_e32 v89, 0xffff0000, v45
	v_pk_mul_f32 v[104:105], v[40:41], v[40:41]
	v_pk_mul_f32 v[100:101], v[88:89], v[88:89]
	v_add_f32_e32 v65, v104, v105
	v_add_f32_e32 v65, v100, v65
	v_pk_mul_f32 v[96:97], v[42:43], v[42:43]
	v_add_f32_e32 v65, v101, v65
	v_add_f32_e32 v65, v96, v65
	v_pk_mul_f32 v[92:93], v[84:85], v[84:85]
	v_add_f32_e32 v65, v97, v65
	v_add_f32_e32 v65, v92, v65
	v_pk_mul_f32 v[102:103], v[90:91], v[90:91]
	v_add_f32_e32 v65, v93, v65
	v_add_f32_e32 v65, v102, v65
	v_pk_mul_f32 v[98:99], v[46:47], v[46:47]
	v_add_f32_e32 v65, v103, v65
	v_add_f32_e32 v65, v98, v65
	v_pk_mul_f32 v[94:95], v[86:87], v[86:87]
	v_add_f32_e32 v65, v99, v65
	v_add_f32_e32 v65, v94, v65
	v_pk_mul_f32 v[44:45], v[80:81], v[80:81]
	v_add_f32_e32 v65, v95, v65
	v_add_f32_e32 v44, v44, v65
	v_add_f32_e32 v44, v45, v44
	ds_bpermute_b32 v45, v60, v44
	s_add_i32 s12, s12, s13
	s_add_i32 s21, s21, s20
	v_lshl_add_u64 v[78:79], v[78:79], 0, v[34:35]
	s_waitcnt lgkmcnt(0)
	v_add_f32_e32 v44, v44, v45
	ds_bpermute_b32 v45, v61, v44
	s_waitcnt lgkmcnt(0)
	v_add_f32_e32 v44, v44, v45
	ds_bpermute_b32 v45, v62, v44
	s_waitcnt lgkmcnt(0)
	v_add_f32_e32 v44, v44, v45
	v_fmamk_f32 v44, v44, 0x3c000000, v64
	v_rsq_f32_e32 v44, v44
	s_nop 0
	v_pk_mul_f32 v[40:41], v[44:45], v[40:41] op_sel_hi:[0,1]
	v_pk_mul_f32 v[88:89], v[44:45], v[88:89] op_sel_hi:[0,1]
	v_pk_mul_f32 v[42:43], v[44:45], v[42:43] op_sel_hi:[0,1]
	v_pk_mul_f32 v[84:85], v[44:45], v[84:85] op_sel_hi:[0,1]
	v_pk_mul_f32 v[90:91], v[44:45], v[90:91] op_sel_hi:[0,1]
	v_pk_mul_f32 v[46:47], v[44:45], v[46:47] op_sel_hi:[0,1]
	v_pk_mul_f32 v[86:87], v[44:45], v[86:87] op_sel_hi:[0,1]
	v_pk_mul_f32 v[44:45], v[44:45], v[80:81] op_sel_hi:[0,1]
	v_pk_mul_f32 v[40:41], v[2:3], v[40:41]
	v_pk_mul_f32 v[88:89], v[4:5], v[88:89]
	v_pk_mul_f32 v[42:43], v[6:7], v[42:43]
	v_pk_mul_f32 v[84:85], v[8:9], v[84:85]
	v_pk_mul_f32 v[80:81], v[10:11], v[90:91]
	v_pk_mul_f32 v[46:47], v[12:13], v[46:47]
	v_pk_mul_f32 v[86:87], v[14:15], v[86:87]
	v_pk_mul_f32 v[44:45], v[16:17], v[44:45]
	v_pk_mul_f32 v[40:41], v[74:75], v[40:41]
	v_pk_mul_f32 v[48:49], v[48:49], v[88:89]
	v_pk_mul_f32 v[42:43], v[70:71], v[42:43]
	v_pk_mul_f32 v[70:71], v[82:83], v[84:85]
	v_pk_mul_f32 v[66:67], v[66:67], v[80:81]
	v_pk_mul_f32 v[46:47], v[72:73], v[46:47]
	v_pk_mul_f32 v[68:69], v[68:69], v[86:87]
	v_pk_mul_f32 v[72:73], v[76:77], v[44:45]
	v_cvt_pk_bf16_f32 v40, v40, v41
	v_cvt_pk_bf16_f32 v41, v48, v49
	v_cvt_pk_bf16_f32 v42, v42, v43
	v_cvt_pk_bf16_f32 v43, v70, v71
	v_cvt_pk_bf16_f32 v44, v66, v67
	v_cvt_pk_bf16_f32 v45, v46, v47
	v_cvt_pk_bf16_f32 v46, v68, v69
	v_cvt_pk_bf16_f32 v47, v72, v73
	global_store_dwordx4 v[78:79], v[40:43], off
	global_store_dwordx4 v[78:79], v[44:47], off offset:16
	s_barrier
	s_cbranch_vccnz .LBB0_1877
